# glr_panels: all CUs, two waves per 32-row panel (half of K each), partial sums combined through LDS
# speedup vs baseline: 1.0067x; 1.0019x over previous
.LBB0_240:
	s_cmp_lt_i32 s88, 2
	s_cselect_b64 s[0:1], -1, 0
	s_and_b64 s[4:5], s[0:1], s[34:35]
	s_mov_b32 s0, s64
	s_andn2_b64 vcc, exec, s[4:5]
	v_writelane_b32 v238, s0, 4
	s_nop 1
	v_writelane_b32 v238, s1, 5
	s_cbranch_vccnz .LBB0_307
	s_add_u32 s6, s94, 0xa800000
	s_waitcnt lgkmcnt(0)
	v_mov_b32_e32 v1, v208
	s_addc_u32 s7, s95, 0
	s_add_u32 s0, s94, 0x32800000
	v_ashrrev_i32_e32 v0, 6, v1
	v_and_b32_e32 v145, 3, v0
	v_lshl_add_u32 v145, s64, 2, v145
	s_movk_i32 s3, 0x400
	s_addc_u32 s1, s95, 0
	v_cmp_gt_i32_e32 vcc, s3, v145
	s_and_saveexec_b64 s[8:9], vcc
	s_cbranch_execz .LBB0_248
	v_and_b32_e32 v144, 31, v1
	v_bfe_u32 v1, v1, 5, 1
	v_mov_b32_e32 v147, 0
	v_lshlrev_b32_e32 v146, 11, v144
	v_lshl_add_u64 v[148:149], s[94:95], 0, v[146:147]
	v_lshlrev_b32_e32 v146, 4, v1
	v_lshrrev_b32_e32 v2, 8, v208
	v_lshl_add_u32 v146, v2, 10, v146
	v_lshl_add_u64 v[2:3], v[148:149], 0, v[146:147]
	s_mov_b64 s[10:11], 0x1400000
	v_lshlrev_b32_e32 v0, 5, v145
	v_lshl_add_u64 v[150:151], v[2:3], 0, s[10:11]
	v_lshlrev_b32_e32 v2, 2, v144
	v_mov_b32_e32 v3, v147
	v_lshl_add_u64 v[152:153], s[6:7], 0, v[146:147]
	v_lshlrev_b32_e32 v166, 2, v1
	v_lshl_add_u64 v[154:155], s[0:1], 0, v[2:3]
	s_lshl_b32 s3, s90, 3
	v_or_b32_e32 v156, v0, v144
	s_lshl_b32 s16, s90, 8
	s_mov_b64 s[10:11], 0
	s_mov_b32 s17, 0xa800000
	s_mov_b32 s18, 0x1400000
	s_mov_b64 s[12:13], 0x200
	s_movk_i32 s19, 0x3ff
	s_branch .LBB0_244
.LBB0_243:
	v_lshrrev_b32_e32 v16, 8, v208
	v_and_b32_e32 v17, 0xff, v208
	v_readfirstlane_b32 s20, v16
	v_lshlrev_b32_e32 v17, 2, v17
	v_add_u32_e32 v17, 0x20000, v17
	s_nop 7
	s_nop 7
	s_cmp_eq_u32 s20, 0
	s_cbranch_scc1 .Lglr0s_lo
	ds_write_b32 v17, v0
	ds_write_b32 v17, v1 offset:1024
	ds_write_b32 v17, v2 offset:2048
	ds_write_b32 v17, v3 offset:3072
	ds_write_b32 v17, v4 offset:4096
	ds_write_b32 v17, v5 offset:5120
	ds_write_b32 v17, v6 offset:6144
	ds_write_b32 v17, v7 offset:7168
	ds_write_b32 v17, v8 offset:8192
	ds_write_b32 v17, v9 offset:9216
	ds_write_b32 v17, v10 offset:10240
	ds_write_b32 v17, v11 offset:11264
	ds_write_b32 v17, v12 offset:12288
	ds_write_b32 v17, v13 offset:13312
	ds_write_b32 v17, v14 offset:14336
	ds_write_b32 v17, v15 offset:15360
	s_waitcnt lgkmcnt(0)
	s_barrier
	s_branch .LBB0_248
.Lglr0s_lo:
	s_barrier
	ds_read_b32 v18, v17
	ds_read_b32 v19, v17 offset:1024
	ds_read_b32 v20, v17 offset:2048
	ds_read_b32 v21, v17 offset:3072
	ds_read_b32 v22, v17 offset:4096
	ds_read_b32 v23, v17 offset:5120
	ds_read_b32 v24, v17 offset:6144
	ds_read_b32 v25, v17 offset:7168
	ds_read_b32 v26, v17 offset:8192
	ds_read_b32 v27, v17 offset:9216
	ds_read_b32 v28, v17 offset:10240
	ds_read_b32 v29, v17 offset:11264
	ds_read_b32 v30, v17 offset:12288
	ds_read_b32 v31, v17 offset:13312
	ds_read_b32 v32, v17 offset:14336
	ds_read_b32 v33, v17 offset:15360
	s_waitcnt lgkmcnt(0)
	v_add_f32_e32 v0, v0, v18
	v_add_f32_e32 v1, v1, v19
	v_add_f32_e32 v2, v2, v20
	v_add_f32_e32 v3, v3, v21
	v_add_f32_e32 v4, v4, v22
	v_add_f32_e32 v5, v5, v23
	v_add_f32_e32 v6, v6, v24
	v_add_f32_e32 v7, v7, v25
	v_add_f32_e32 v8, v8, v26
	v_add_f32_e32 v9, v9, v27
	v_add_f32_e32 v10, v10, v28
	v_add_f32_e32 v11, v11, v29
	v_add_f32_e32 v12, v12, v30
	v_add_f32_e32 v13, v13, v31
	v_add_f32_e32 v14, v14, v32
	v_add_f32_e32 v15, v15, v33
	v_or_b32_e32 v16, v167, v166
	v_ashrrev_i32_e32 v17, 31, v16
	v_lshlrev_b64 v[18:19], 7, v[16:17]
	v_lshl_add_u64 v[18:19], v[154:155], 0, v[18:19]
	s_nop 6
	global_store_dword v[18:19], v0, off
	v_or_b32_e32 v18, 1, v16
	v_ashrrev_i32_e32 v19, 31, v18
	v_lshlrev_b64 v[18:19], 7, v[18:19]
	v_lshl_add_u64 v[18:19], v[154:155], 0, v[18:19]
	v_or_b32_e32 v0, 2, v16
	global_store_dword v[18:19], v1, off
	v_ashrrev_i32_e32 v1, 31, v0
	v_lshlrev_b64 v[0:1], 7, v[0:1]
	v_lshl_add_u64 v[0:1], v[154:155], 0, v[0:1]
	global_store_dword v[0:1], v2, off
	v_or_b32_e32 v0, 3, v16
	v_ashrrev_i32_e32 v1, 31, v0
	v_lshlrev_b64 v[0:1], 7, v[0:1]
	v_lshl_add_u64 v[0:1], v[154:155], 0, v[0:1]
	global_store_dword v[0:1], v3, off
	v_or_b32_e32 v0, 8, v16
	v_ashrrev_i32_e32 v1, 31, v0
	v_lshlrev_b64 v[0:1], 7, v[0:1]
	v_lshl_add_u64 v[0:1], v[154:155], 0, v[0:1]
	global_store_dword v[0:1], v4, off
	v_or_b32_e32 v0, 9, v16
	v_ashrrev_i32_e32 v1, 31, v0
	v_lshlrev_b64 v[0:1], 7, v[0:1]
	v_lshl_add_u64 v[0:1], v[154:155], 0, v[0:1]
	global_store_dword v[0:1], v5, off
	v_or_b32_e32 v0, 10, v16
	v_ashrrev_i32_e32 v1, 31, v0
	v_lshlrev_b64 v[0:1], 7, v[0:1]
	v_lshl_add_u64 v[0:1], v[154:155], 0, v[0:1]
	global_store_dword v[0:1], v6, off
	v_or_b32_e32 v0, 11, v16
	v_ashrrev_i32_e32 v1, 31, v0
	v_lshlrev_b64 v[0:1], 7, v[0:1]
	v_lshl_add_u64 v[0:1], v[154:155], 0, v[0:1]
	global_store_dword v[0:1], v7, off
	v_or_b32_e32 v0, 16, v16
	v_ashrrev_i32_e32 v1, 31, v0
	v_lshlrev_b64 v[0:1], 7, v[0:1]
	v_lshl_add_u64 v[0:1], v[154:155], 0, v[0:1]
	global_store_dword v[0:1], v8, off
	v_or_b32_e32 v0, 17, v16
	v_ashrrev_i32_e32 v1, 31, v0
	v_lshlrev_b64 v[0:1], 7, v[0:1]
	v_lshl_add_u64 v[0:1], v[154:155], 0, v[0:1]
	global_store_dword v[0:1], v9, off
	v_or_b32_e32 v0, 18, v16
	v_ashrrev_i32_e32 v1, 31, v0
	v_lshlrev_b64 v[0:1], 7, v[0:1]
	v_lshl_add_u64 v[0:1], v[154:155], 0, v[0:1]
	global_store_dword v[0:1], v10, off
	v_or_b32_e32 v0, 19, v16
	v_ashrrev_i32_e32 v1, 31, v0
	v_lshlrev_b64 v[0:1], 7, v[0:1]
	v_lshl_add_u64 v[0:1], v[154:155], 0, v[0:1]
	global_store_dword v[0:1], v11, off
	v_or_b32_e32 v0, 24, v16
	v_ashrrev_i32_e32 v1, 31, v0
	v_lshlrev_b64 v[0:1], 7, v[0:1]
	v_lshl_add_u64 v[0:1], v[154:155], 0, v[0:1]
	global_store_dword v[0:1], v12, off
	v_or_b32_e32 v0, 25, v16
	v_ashrrev_i32_e32 v1, 31, v0
	v_lshlrev_b64 v[0:1], 7, v[0:1]
	v_lshl_add_u64 v[0:1], v[154:155], 0, v[0:1]
	global_store_dword v[0:1], v13, off
	v_or_b32_e32 v0, 26, v16
	v_ashrrev_i32_e32 v1, 31, v0
	v_lshlrev_b64 v[0:1], 7, v[0:1]
	v_lshl_add_u64 v[0:1], v[154:155], 0, v[0:1]
	global_store_dword v[0:1], v14, off
	v_or_b32_e32 v0, 27, v16
	v_ashrrev_i32_e32 v1, 31, v0
	v_lshlrev_b64 v[0:1], 7, v[0:1]
	v_lshl_add_u64 v[0:1], v[154:155], 0, v[0:1]
	global_store_dword v[0:1], v15, off
	s_branch .LBB0_248

.LBB0_246:
	v_lshl_add_u64 v[164:165], v[158:159], 0, v[146:147]
	v_add_co_u32_e32 v80, vcc, s17, v164
	v_lshl_add_u64 v[162:163], v[160:161], 0, v[146:147]
	s_nop 0
	v_addc_co_u32_e32 v81, vcc, 0, v165, vcc
	v_add_co_u32_e32 v100, vcc, s18, v162
	global_load_dwordx4 v[96:99], v[80:81], off offset:256
	global_load_dwordx4 v[92:95], v[80:81], off offset:288
	global_load_dwordx4 v[88:91], v[80:81], off offset:320
	global_load_dwordx4 v[84:87], v[80:81], off offset:352
	v_addc_co_u32_e32 v101, vcc, 0, v163, vcc
	global_load_dwordx4 v[112:115], v[80:81], off offset:384
	global_load_dwordx4 v[108:111], v[80:81], off offset:416
	global_load_dwordx4 v[104:107], v[80:81], off offset:448
	s_nop 0
	global_load_dwordx4 v[80:83], v[80:81], off offset:480
	s_nop 0
	global_load_dwordx4 v[140:143], v[100:101], off offset:256
	global_load_dwordx4 v[136:139], v[100:101], off offset:288
	global_load_dwordx4 v[132:135], v[100:101], off offset:320
	global_load_dwordx4 v[124:127], v[100:101], off offset:352
	global_load_dwordx4 v[128:131], v[100:101], off offset:384
	global_load_dwordx4 v[120:123], v[100:101], off offset:416
	global_load_dwordx4 v[116:119], v[100:101], off offset:448
	s_nop 0
	global_load_dwordx4 v[100:103], v[100:101], off offset:480
	s_waitcnt vmcnt(29)
	v_mfma_f32_32x32x16_bf16 v[0:15], v[16:19], v[24:27], v[0:15]
	s_cmp_gt_u32 s20, 15
	s_cselect_b64 s[14:15], -1, 0
	s_and_b64 vcc, exec, s[14:15]
	s_waitcnt vmcnt(28)
	v_mfma_f32_32x32x16_bf16 v[0:15], v[20:23], v[28:31], v[0:15]
	s_waitcnt vmcnt(25)
	v_mfma_f32_32x32x16_bf16 v[0:15], v[32:35], v[40:43], v[0:15]
	s_waitcnt vmcnt(24)
	v_mfma_f32_32x32x16_bf16 v[0:15], v[36:39], v[44:47], v[0:15]
	s_waitcnt vmcnt(21)
	v_mfma_f32_32x32x16_bf16 v[0:15], v[48:51], v[56:59], v[0:15]
	s_waitcnt vmcnt(20)
	v_mfma_f32_32x32x16_bf16 v[0:15], v[52:55], v[60:63], v[0:15]
	s_waitcnt vmcnt(17)
	v_mfma_f32_32x32x16_bf16 v[0:15], v[64:67], v[72:75], v[0:15]
	s_waitcnt vmcnt(16)
	v_mfma_f32_32x32x16_bf16 v[0:15], v[68:71], v[76:79], v[0:15]
	s_cbranch_vccnz .LBB0_245
	v_add_co_u32_e32 v68, vcc, 0xa800000, v164
	s_nop 1
	v_addc_co_u32_e32 v69, vcc, 0, v165, vcc
	v_add_co_u32_e32 v76, vcc, 0x1400000, v162
	s_nop 1
	v_addc_co_u32_e32 v77, vcc, 0, v163, vcc
	global_load_dwordx4 v[16:19], v[68:69], off offset:512
	global_load_dwordx4 v[20:23], v[68:69], off offset:544
	global_load_dwordx4 v[24:27], v[76:77], off offset:512
	global_load_dwordx4 v[28:31], v[76:77], off offset:544
	global_load_dwordx4 v[32:35], v[68:69], off offset:576
	global_load_dwordx4 v[36:39], v[68:69], off offset:608
	global_load_dwordx4 v[40:43], v[76:77], off offset:576
	global_load_dwordx4 v[44:47], v[76:77], off offset:608
	global_load_dwordx4 v[48:51], v[68:69], off offset:640
	global_load_dwordx4 v[52:55], v[68:69], off offset:672
	global_load_dwordx4 v[56:59], v[76:77], off offset:640
	global_load_dwordx4 v[60:63], v[76:77], off offset:672
	global_load_dwordx4 v[64:67], v[68:69], off offset:704
	s_nop 0
	global_load_dwordx4 v[68:71], v[68:69], off offset:736
	s_nop 0
	global_load_dwordx4 v[72:75], v[76:77], off offset:704
	s_nop 0
	global_load_dwordx4 v[76:79], v[76:77], off offset:736
	s_branch .Lglr0_b

.LBB0_633:
	s_cmp_lt_i32 s88, 6
	s_cselect_b64 s[4:5], -1, 0
	s_and_b64 s[4:5], s[4:5], s[0:1]
	s_andn2_b64 vcc, exec, s[4:5]
	s_cbranch_vccnz .LBB0_700
	s_add_u32 s6, s94, 0xe800000
	s_waitcnt lgkmcnt(0)
	v_mov_b32_e32 v1, v208
	s_addc_u32 s7, s95, 0
	s_add_u32 s0, s94, 0x32800000
	v_ashrrev_i32_e32 v0, 6, v1
	v_and_b32_e32 v145, 3, v0
	v_lshl_add_u32 v145, s64, 2, v145
	s_movk_i32 s3, 0x400
	s_addc_u32 s1, s95, 0
	v_cmp_gt_i32_e32 vcc, s3, v145
	s_and_saveexec_b64 s[8:9], vcc
	s_cbranch_execz .LBB0_641
	v_and_b32_e32 v144, 31, v1
	v_bfe_u32 v1, v1, 5, 1
	v_mov_b32_e32 v147, 0
	v_lshlrev_b32_e32 v146, 11, v144
	v_lshl_add_u64 v[148:149], s[94:95], 0, v[146:147]
	v_lshlrev_b32_e32 v146, 4, v1
	v_lshrrev_b32_e32 v2, 8, v208
	v_lshl_add_u32 v146, v2, 10, v146
	v_lshl_add_u64 v[2:3], v[148:149], 0, v[146:147]
	s_mov_b64 s[10:11], 0x1400000
	v_lshlrev_b32_e32 v0, 5, v145
	v_lshl_add_u64 v[150:151], v[2:3], 0, s[10:11]
	v_lshlrev_b32_e32 v2, 2, v144
	v_mov_b32_e32 v3, v147
	v_lshl_add_u64 v[152:153], s[6:7], 0, v[146:147]
	v_lshlrev_b32_e32 v166, 2, v1
	v_lshl_add_u64 v[154:155], s[0:1], 0, v[2:3]
	s_lshl_b32 s3, s90, 3
	v_or_b32_e32 v156, v0, v144
	s_lshl_b32 s16, s90, 8
	s_mov_b64 s[10:11], 0
	s_mov_b32 s17, 0xe800000
	s_mov_b32 s18, 0x1400000
	s_mov_b64 s[12:13], 0x200
	s_movk_i32 s19, 0x3ff
	s_branch .LBB0_637

.LBB0_639:
	v_lshl_add_u64 v[164:165], v[158:159], 0, v[146:147]
	v_add_co_u32_e32 v80, vcc, s17, v164
	v_lshl_add_u64 v[162:163], v[160:161], 0, v[146:147]
	s_nop 0
	v_addc_co_u32_e32 v81, vcc, 0, v165, vcc
	v_add_co_u32_e32 v84, vcc, s18, v162
	s_waitcnt vmcnt(0)
	v_mfma_f32_32x32x16_bf16 v[0:15], v[16:19], v[24:27], v[0:15]
	v_addc_co_u32_e32 v85, vcc, 0, v163, vcc
	global_load_dwordx4 v[96:99], v[80:81], off offset:256
	global_load_dwordx4 v[88:91], v[80:81], off offset:288
	global_load_dwordx4 v[108:111], v[84:85], off offset:256
	global_load_dwordx4 v[104:107], v[84:85], off offset:288
	global_load_dwordx4 v[100:103], v[80:81], off offset:320
	global_load_dwordx4 v[92:95], v[80:81], off offset:352
	global_load_dwordx4 v[132:135], v[84:85], off offset:320
	global_load_dwordx4 v[124:127], v[84:85], off offset:352
	global_load_dwordx4 v[116:119], v[80:81], off offset:384
	global_load_dwordx4 v[112:115], v[80:81], off offset:416
	global_load_dwordx4 v[136:139], v[84:85], off offset:384
	global_load_dwordx4 v[128:131], v[84:85], off offset:416
	global_load_dwordx4 v[120:123], v[80:81], off offset:448
	s_nop 0
	global_load_dwordx4 v[80:83], v[80:81], off offset:480
	s_nop 0
	global_load_dwordx4 v[140:143], v[84:85], off offset:448
	s_nop 0
	global_load_dwordx4 v[84:87], v[84:85], off offset:480
	s_cmp_gt_u32 s20, 15
	s_cselect_b64 s[14:15], -1, 0
	v_mfma_f32_32x32x16_bf16 v[0:15], v[20:23], v[28:31], v[0:15]
	s_and_b64 vcc, exec, s[14:15]
	v_mfma_f32_32x32x16_bf16 v[0:15], v[32:35], v[40:43], v[0:15]
	v_mfma_f32_32x32x16_bf16 v[0:15], v[36:39], v[44:47], v[0:15]
	v_mfma_f32_32x32x16_bf16 v[0:15], v[48:51], v[56:59], v[0:15]
	v_mfma_f32_32x32x16_bf16 v[0:15], v[52:55], v[60:63], v[0:15]
	v_mfma_f32_32x32x16_bf16 v[0:15], v[64:67], v[72:75], v[0:15]
	v_mfma_f32_32x32x16_bf16 v[0:15], v[68:71], v[76:79], v[0:15]
	s_cbranch_vccnz .LBB0_638
	v_add_co_u32_e32 v68, vcc, 0xe800000, v164
	s_nop 1
	v_addc_co_u32_e32 v69, vcc, 0, v165, vcc
	v_add_co_u32_e32 v76, vcc, 0x1400000, v162
	s_nop 1
	v_addc_co_u32_e32 v77, vcc, 0, v163, vcc
	global_load_dwordx4 v[16:19], v[68:69], off offset:512
	global_load_dwordx4 v[20:23], v[68:69], off offset:544
	global_load_dwordx4 v[24:27], v[76:77], off offset:512
	global_load_dwordx4 v[28:31], v[76:77], off offset:544
	global_load_dwordx4 v[32:35], v[68:69], off offset:576
	global_load_dwordx4 v[36:39], v[68:69], off offset:608
	global_load_dwordx4 v[40:43], v[76:77], off offset:576
	global_load_dwordx4 v[44:47], v[76:77], off offset:608
	global_load_dwordx4 v[48:51], v[68:69], off offset:640
	global_load_dwordx4 v[52:55], v[68:69], off offset:672
	global_load_dwordx4 v[56:59], v[76:77], off offset:640
	global_load_dwordx4 v[60:63], v[76:77], off offset:672
	global_load_dwordx4 v[64:67], v[68:69], off offset:704
	s_nop 0
	global_load_dwordx4 v[68:71], v[68:69], off offset:736
	s_nop 0
	global_load_dwordx4 v[72:75], v[76:77], off offset:704
	s_nop 0
	global_load_dwordx4 v[76:79], v[76:77], off offset:736
	s_branch .Lglr1_b
